# row quantisation loop after FFN1-down: next row and its sum of squares prefetched into staging registers
# baseline (speedup 1.0000x reference)
.LBB0_571:
	s_or_b64 exec, exec, s[0:1]
	s_waitcnt lgkmcnt(0)
	v_mov_b32_e32 v0, v190
	s_barrier
	s_nop 0
	v_readfirstlane_b32 s0, v0
	s_ashr_i32 s2, s0, 6
	v_readlane_b32 s0, v251, 38
	s_add_i32 s6, s2, s0
	s_cmpk_gt_i32 s6, 0x3fff
	s_cbranch_scc1 .LBB0_576
	v_mbcnt_hi_u32_b32 v3, -1, v166
	v_and_b32_e32 v1, 64, v3
	v_add_u32_e32 v4, 64, v1
	v_xor_b32_e32 v5, 1, v3
	v_cmp_lt_i32_e32 vcc, v5, v4
	v_readlane_b32 s5, v251, 38
	s_ashr_i32 s3, s2, 31
	v_cndmask_b32_e32 v5, v3, v5, vcc
	v_lshlrev_b32_e32 v6, 2, v5
	v_xor_b32_e32 v5, 2, v3
	v_cmp_lt_i32_e32 vcc, v5, v4
	s_ashr_i32 s4, s5, 31
	s_add_u32 s2, s2, s5
	v_cndmask_b32_e32 v5, v3, v5, vcc
	v_lshlrev_b32_e32 v7, 2, v5
	v_xor_b32_e32 v5, 4, v3
	v_cmp_lt_i32_e32 vcc, v5, v4
	s_addc_u32 s3, s3, s4
	v_readlane_b32 s16, v251, 8
	v_cndmask_b32_e32 v5, v3, v5, vcc
	v_lshlrev_b32_e32 v8, 2, v5
	v_xor_b32_e32 v5, 8, v3
	v_cmp_lt_i32_e32 vcc, v5, v4
	s_lshl_b64 s[4:5], s[2:3], 2
	v_readlane_b32 s22, v251, 14
	v_cndmask_b32_e32 v5, v3, v5, vcc
	v_lshlrev_b32_e32 v9, 2, v5
	v_xor_b32_e32 v5, 16, v3
	v_cmp_lt_i32_e32 vcc, v5, v4
	v_readlane_b32 s23, v251, 15
	s_add_u32 s4, s22, s4
	v_cndmask_b32_e32 v5, v3, v5, vcc
	v_readlane_b32 s8, v252, 5
	v_lshlrev_b32_e32 v10, 2, v5
	v_xor_b32_e32 v5, 32, v3
	s_addc_u32 s5, s23, s5
	v_readlane_b32 s9, v252, 6
	s_mov_b32 s14, s8
	s_ashr_i32 s15, s8, 31
	v_cmp_lt_i32_e32 vcc, v5, v4
	s_lshl_b64 s[8:9], s[14:15], 2
	s_lshl_b64 s[10:11], s[2:3], 12
	v_and_b32_e32 v2, 63, v0
	v_mov_b32_e32 v1, 0
	v_cndmask_b32_e32 v3, v3, v5, vcc
	s_add_u32 s10, s22, s10
	v_lshlrev_b32_e32 v0, 3, v2
	v_cmp_eq_u32_e64 s[0:1], 0, v2
	v_lshlrev_b32_e32 v11, 2, v3
	v_lshlrev_b32_e32 v2, 4, v2
	v_mov_b32_e32 v3, v1
	s_addc_u32 s11, s23, s11
	v_lshl_add_u64 v[2:3], s[10:11], 0, v[2:3]
	s_mov_b64 s[10:11], 0xa600800
	v_lshl_add_u64 v[2:3], v[2:3], 0, s[10:11]
	s_lshl_b64 s[10:11], s[14:15], 12
	s_lshl_b64 s[2:3], s[2:3], 11
	s_add_u32 s2, s22, s2
	s_addc_u32 s3, s23, s3
	v_lshl_add_u64 v[4:5], s[2:3], 0, v[0:1]
	s_mov_b64 s[2:3], 0x3000400
	v_lshl_add_u64 v[4:5], v[4:5], 0, s[2:3]
	s_mov_b32 s2, s14
	v_readlane_b32 s20, v251, 12
	v_readlane_b32 s21, v251, 13
	v_writelane_b32 v252, s2, 5
	s_lshl_b64 s[20:21], s[14:15], 11
	s_mov_b32 s7, 0xda24260
	v_writelane_b32 v252, s3, 6
	s_mov_b32 s12, 0x42fe0000
	s_mov_b32 s14, 0xc2fe0000
	v_mov_b32_e32 v0, 0x42fe0000
	s_mov_b32 s15, 0x40c0c00
	v_mov_b32_e32 v12, 0x10000
	v_mov_b32_e32 v13, 0x358637bd
	s_mov_b32 s16, 0x800000
	v_readlane_b32 s17, v251, 9
	v_readlane_b32 s18, v251, 10
	v_readlane_b32 s19, v251, 11
	global_load_dwordx4 v[80:83], v[2:3], off offset:-2048
	global_load_dwordx4 v[84:87], v[2:3], off offset:-1024
	global_load_dwordx4 v[88:91], v[2:3], off
	global_load_dwordx4 v[92:95], v[2:3], off offset:1024
	global_load_dword v96, v12, s[4:5]
	s_waitcnt vmcnt(0)
	s_branch .LBB0_574

.LBB0_574:
	s_waitcnt vmcnt(4)
	v_mov_b32_e32 v14, v80
	v_mov_b32_e32 v15, v81
	v_mov_b32_e32 v16, v82
	v_mov_b32_e32 v17, v83
	v_mov_b32_e32 v18, v84
	v_mov_b32_e32 v19, v85
	v_mov_b32_e32 v20, v86
	v_mov_b32_e32 v21, v87
	v_mov_b32_e32 v22, v88
	v_mov_b32_e32 v23, v89
	v_mov_b32_e32 v24, v90
	v_mov_b32_e32 v25, v91
	v_mov_b32_e32 v26, v92
	v_mov_b32_e32 v27, v93
	v_mov_b32_e32 v28, v94
	v_mov_b32_e32 v29, v95
	v_mov_b32_e32 v97, v96
	v_readlane_b32 vcc_lo, v252, 5
	s_add_i32 vcc_lo, s6, vcc_lo
	s_cmpk_gt_i32 vcc_lo, 0x3fff
	s_cbranch_scc1 .Lrq_nopf
	v_lshl_add_u64 v[98:99], v[2:3], 0, s[10:11]
	global_load_dwordx4 v[80:83], v[98:99], off offset:-2048
	global_load_dwordx4 v[84:87], v[98:99], off offset:-1024
	global_load_dwordx4 v[88:91], v[98:99], off
	global_load_dwordx4 v[92:95], v[98:99], off offset:1024
	v_add_u32_e32 v100, s8, v12
	global_load_dword v96, v100, s[4:5]
.Lrq_nopf:
	v_lshlrev_b32_e32 v30, 16, v14
	v_and_b32_e32 v31, 0xffff0000, v14
	v_lshlrev_b32_e32 v33, 16, v16
	v_and_b32_e32 v16, 0xffff0000, v16
	v_lshlrev_b32_e32 v32, 16, v15
	v_and_b32_e32 v15, 0xffff0000, v15
	v_lshlrev_b32_e32 v34, 16, v17
	v_and_b32_e32 v17, 0xffff0000, v17
	v_max_f32_e64 v14, |v33|, |v33|
	v_max_f32_e64 v47, |v30|, |v30|
	v_max_f32_e64 v48, |v16|, |v16|
	v_max_f32_e64 v49, |v31|, |v31|
	v_lshlrev_b32_e32 v35, 16, v18
	v_and_b32_e32 v18, 0xffff0000, v18
	v_lshlrev_b32_e32 v37, 16, v20
	v_and_b32_e32 v20, 0xffff0000, v20
	v_max_f32_e64 v50, |v34|, |v34|
	v_max_f32_e64 v51, |v32|, |v32|
	v_max_f32_e64 v52, |v17|, |v17|
	v_max_f32_e64 v53, |v15|, |v15|
	v_max_f32_e32 v14, v47, v14
	v_max_f32_e32 v47, v49, v48
	v_lshlrev_b32_e32 v36, 16, v19
	v_and_b32_e32 v19, 0xffff0000, v19
	v_lshlrev_b32_e32 v38, 16, v21
	v_and_b32_e32 v21, 0xffff0000, v21
	v_max_f32_e64 v54, |v37|, |v37|
	v_max_f32_e64 v55, |v35|, |v35|
	v_max_f32_e64 v56, |v20|, |v20|
	v_max_f32_e64 v57, |v18|, |v18|
	v_max_f32_e32 v48, v51, v50
	v_max_f32_e32 v49, v53, v52
	v_max3_f32 v14, v14, 0, v47
	v_lshlrev_b32_e32 v39, 16, v22
	v_and_b32_e32 v22, 0xffff0000, v22
	v_lshlrev_b32_e32 v41, 16, v24
	v_and_b32_e32 v24, 0xffff0000, v24
	v_max_f32_e64 v58, |v38|, |v38|
	v_max_f32_e64 v59, |v36|, |v36|
	v_max_f32_e64 v60, |v21|, |v21|
	v_max_f32_e64 v61, |v19|, |v19|
	v_max_f32_e32 v50, v55, v54
	v_max_f32_e32 v51, v57, v56
	v_max3_f32 v14, v14, v48, v49
	v_lshlrev_b32_e32 v40, 16, v23
	v_and_b32_e32 v23, 0xffff0000, v23
	v_lshlrev_b32_e32 v42, 16, v25
	v_and_b32_e32 v25, 0xffff0000, v25
	v_max_f32_e64 v62, |v41|, |v41|
	v_max_f32_e64 v63, |v39|, |v39|
	v_max_f32_e64 v64, |v24|, |v24|
	v_max_f32_e64 v65, |v22|, |v22|
	v_max_f32_e32 v52, v59, v58
	v_max_f32_e32 v53, v61, v60
	v_max3_f32 v14, v14, v50, v51
	v_lshlrev_b32_e32 v43, 16, v26
	v_and_b32_e32 v26, 0xffff0000, v26
	v_lshlrev_b32_e32 v45, 16, v28
	v_and_b32_e32 v28, 0xffff0000, v28
	v_max_f32_e64 v66, |v42|, |v42|
	v_max_f32_e64 v67, |v40|, |v40|
	v_max_f32_e64 v68, |v25|, |v25|
	v_max_f32_e64 v69, |v23|, |v23|
	v_max_f32_e32 v54, v63, v62
	v_max_f32_e32 v55, v65, v64
	v_max3_f32 v14, v14, v52, v53
	v_lshlrev_b32_e32 v44, 16, v27
	v_and_b32_e32 v27, 0xffff0000, v27
	v_lshlrev_b32_e32 v46, 16, v29
	v_and_b32_e32 v29, 0xffff0000, v29
	v_max_f32_e64 v70, |v45|, |v45|
	v_max_f32_e64 v71, |v43|, |v43|
	v_max_f32_e64 v72, |v28|, |v28|
	v_max_f32_e64 v73, |v26|, |v26|
	v_max_f32_e32 v56, v67, v66
	v_max_f32_e32 v57, v69, v68
	v_max3_f32 v14, v14, v54, v55
	v_max_f32_e64 v74, |v46|, |v46|
	v_max_f32_e64 v75, |v44|, |v44|
	v_max_f32_e64 v76, |v29|, |v29|
	v_max_f32_e64 v77, |v27|, |v27|
	v_max_f32_e32 v58, v71, v70
	v_max_f32_e32 v59, v73, v72
	v_max3_f32 v14, v14, v56, v57
	v_max_f32_e32 v60, v75, v74
	v_max3_f32 v14, v14, v58, v59
	v_max_f32_e32 v47, v77, v76
	v_max3_f32 v14, v14, v60, v47
	ds_bpermute_b32 v47, v6, v14
	s_waitcnt lgkmcnt(0)
	v_max_f32_e32 v47, v47, v47
	v_max_f32_e32 v14, v14, v47
	ds_bpermute_b32 v47, v7, v14
	s_waitcnt lgkmcnt(0)
	v_max_f32_e32 v47, v47, v47
	v_max_f32_e32 v14, v14, v47
	ds_bpermute_b32 v47, v8, v14
	s_waitcnt lgkmcnt(0)
	v_max_f32_e32 v47, v47, v47
	v_max_f32_e32 v14, v14, v47
	ds_bpermute_b32 v47, v9, v14
	s_waitcnt lgkmcnt(0)
	v_max_f32_e32 v47, v47, v47
	v_max_f32_e32 v14, v14, v47
	ds_bpermute_b32 v47, v10, v14
	s_waitcnt lgkmcnt(0)
	v_max_f32_e32 v47, v47, v47
	v_max_f32_e32 v14, v14, v47
	ds_bpermute_b32 v47, v11, v14
	s_waitcnt lgkmcnt(0)
	v_max3_f32 v14, v14, v47, s7
	v_div_scale_f32 v47, s[2:3], v14, v14, s12
	v_rcp_f32_e32 v48, v47
	v_div_scale_f32 v49, vcc, s12, v14, s12
	v_fma_f32 v50, -v47, v48, 1.0
	v_fmac_f32_e32 v48, v50, v48
	v_mul_f32_e32 v50, v49, v48
	v_fma_f32 v51, -v47, v50, v49
	v_fmac_f32_e32 v50, v51, v48
	v_fma_f32 v47, -v47, v50, v49
	v_div_fmas_f32 v47, v47, v48, v50
	v_div_fixup_f32 v47, v47, v14, s12
	v_mul_f32_e32 v31, v47, v31
	v_mul_f32_e32 v30, v47, v30
	v_mul_f32_e32 v32, v47, v32
	v_mul_f32_e32 v15, v47, v15
	v_med3_f32 v31, v31, s14, v0
	v_med3_f32 v30, v30, s14, v0
	v_med3_f32 v32, v32, s14, v0
	v_med3_f32 v15, v15, s14, v0
	v_rndne_f32_e32 v31, v31
	v_rndne_f32_e32 v30, v30
	v_rndne_f32_e32 v32, v32
	v_rndne_f32_e32 v15, v15
	v_cvt_i32_f32_e32 v31, v31
	v_mul_f32_e32 v16, v47, v16
	v_cvt_i32_f32_e32 v30, v30
	v_cvt_i32_f32_sdwa v32, v32 dst_sel:WORD_1 dst_unused:UNUSED_PAD src0_sel:DWORD
	v_cvt_i32_f32_e32 v15, v15
	v_med3_f32 v16, v16, s14, v0
	v_rndne_f32_e32 v16, v16
	v_mul_f32_e32 v33, v47, v33
	v_mul_f32_e32 v34, v47, v34
	v_mul_f32_e32 v17, v47, v17
	v_cvt_i32_f32_e32 v48, v16
	v_lshlrev_b32_e32 v16, 8, v31
	v_med3_f32 v33, v33, s14, v0
	v_med3_f32 v34, v34, s14, v0
	v_and_b32_e32 v31, 0xff0000, v32
	v_perm_b32 v15, v15, v30, s15
	v_and_b32_e32 v16, 0xff00, v16
	v_med3_f32 v17, v17, s14, v0
	v_rndne_f32_e32 v33, v33
	v_or3_b32 v16, v15, v16, v31
	v_rndne_f32_e32 v15, v34
	v_rndne_f32_e32 v17, v17
	v_cvt_i32_f32_e32 v33, v33
	v_cvt_i32_f32_sdwa v15, v15 dst_sel:WORD_1 dst_unused:UNUSED_PAD src0_sel:DWORD
	v_cvt_i32_f32_e32 v17, v17
	v_lshlrev_b32_e32 v30, 8, v48
	v_and_b32_e32 v30, 0xff00, v30
	v_and_b32_e32 v15, 0xff0000, v15
	v_perm_b32 v17, v17, v33, s15
	v_or3_b32 v17, v17, v30, v15
	global_store_dwordx2 v[4:5], v[16:17], off offset:-1024
	v_mul_f32_e32 v16, v47, v18
	v_mul_f32_e32 v15, v47, v35
	v_mul_f32_e32 v17, v47, v36
	v_mul_f32_e32 v18, v47, v19
	v_med3_f32 v16, v16, s14, v0
	v_med3_f32 v15, v15, s14, v0
	v_rndne_f32_e32 v16, v16
	v_med3_f32 v17, v17, s14, v0
	v_med3_f32 v18, v18, s14, v0
	v_rndne_f32_e32 v15, v15
	v_cvt_i32_f32_e32 v16, v16
	v_rndne_f32_e32 v17, v17
	v_rndne_f32_e32 v18, v18
	v_cvt_i32_f32_e32 v15, v15
	v_cvt_i32_f32_sdwa v17, v17 dst_sel:WORD_1 dst_unused:UNUSED_PAD src0_sel:DWORD
	v_cvt_i32_f32_e32 v18, v18
	v_lshlrev_b32_e32 v16, 8, v16
	v_and_b32_e32 v16, 0xff00, v16
	v_and_b32_e32 v17, 0xff0000, v17
	v_perm_b32 v15, v18, v15, s15
	v_or3_b32 v16, v15, v16, v17
	v_mul_f32_e32 v17, v47, v20
	v_mul_f32_e32 v15, v47, v37
	v_mul_f32_e32 v18, v47, v38
	v_mul_f32_e32 v19, v47, v21
	v_med3_f32 v17, v17, s14, v0
	v_med3_f32 v15, v15, s14, v0
	v_rndne_f32_e32 v17, v17
	v_med3_f32 v18, v18, s14, v0
	v_med3_f32 v19, v19, s14, v0
	v_rndne_f32_e32 v15, v15
	v_cvt_i32_f32_e32 v17, v17
	v_rndne_f32_e32 v18, v18
	v_rndne_f32_e32 v19, v19
	v_cvt_i32_f32_e32 v15, v15
	v_cvt_i32_f32_sdwa v18, v18 dst_sel:WORD_1 dst_unused:UNUSED_PAD src0_sel:DWORD
	v_cvt_i32_f32_e32 v19, v19
	v_lshlrev_b32_e32 v17, 8, v17
	v_and_b32_e32 v17, 0xff00, v17
	v_and_b32_e32 v18, 0xff0000, v18
	v_perm_b32 v15, v19, v15, s15
	v_or3_b32 v17, v15, v17, v18
	global_store_dwordx2 v[4:5], v[16:17], off offset:-512
	v_mul_f32_e32 v16, v47, v22
	v_mul_f32_e32 v15, v47, v39
	v_mul_f32_e32 v17, v47, v40
	v_mul_f32_e32 v18, v47, v23
	v_med3_f32 v16, v16, s14, v0
	v_med3_f32 v15, v15, s14, v0
	v_rndne_f32_e32 v16, v16
	v_med3_f32 v17, v17, s14, v0
	v_med3_f32 v18, v18, s14, v0
	v_rndne_f32_e32 v15, v15
	v_cvt_i32_f32_e32 v16, v16
	v_rndne_f32_e32 v17, v17
	v_rndne_f32_e32 v18, v18
	v_cvt_i32_f32_e32 v15, v15
	v_cvt_i32_f32_sdwa v17, v17 dst_sel:WORD_1 dst_unused:UNUSED_PAD src0_sel:DWORD
	v_cvt_i32_f32_e32 v18, v18
	v_lshlrev_b32_e32 v16, 8, v16
	v_and_b32_e32 v16, 0xff00, v16
	v_and_b32_e32 v17, 0xff0000, v17
	v_perm_b32 v15, v18, v15, s15
	v_or3_b32 v16, v15, v16, v17
	v_mul_f32_e32 v17, v47, v24
	v_mul_f32_e32 v15, v47, v41
	v_mul_f32_e32 v18, v47, v42
	v_mul_f32_e32 v19, v47, v25
	v_med3_f32 v17, v17, s14, v0
	v_med3_f32 v15, v15, s14, v0
	v_rndne_f32_e32 v17, v17
	v_med3_f32 v18, v18, s14, v0
	v_med3_f32 v19, v19, s14, v0
	v_rndne_f32_e32 v15, v15
	v_cvt_i32_f32_e32 v17, v17
	v_rndne_f32_e32 v18, v18
	v_rndne_f32_e32 v19, v19
	v_cvt_i32_f32_e32 v15, v15
	v_cvt_i32_f32_sdwa v18, v18 dst_sel:WORD_1 dst_unused:UNUSED_PAD src0_sel:DWORD
	v_cvt_i32_f32_e32 v19, v19
	v_lshlrev_b32_e32 v17, 8, v17
	v_and_b32_e32 v17, 0xff00, v17
	v_and_b32_e32 v18, 0xff0000, v18
	v_perm_b32 v15, v19, v15, s15
	v_or3_b32 v17, v15, v17, v18
	global_store_dwordx2 v[4:5], v[16:17], off
	v_mul_f32_e32 v16, v47, v26
	v_mul_f32_e32 v15, v47, v43
	v_mul_f32_e32 v17, v47, v44
	v_mul_f32_e32 v18, v47, v27
	v_med3_f32 v16, v16, s14, v0
	v_med3_f32 v15, v15, s14, v0
	v_rndne_f32_e32 v16, v16
	v_med3_f32 v17, v17, s14, v0
	v_med3_f32 v18, v18, s14, v0
	v_rndne_f32_e32 v15, v15
	v_cvt_i32_f32_e32 v16, v16
	v_rndne_f32_e32 v17, v17
	v_rndne_f32_e32 v18, v18
	v_cvt_i32_f32_e32 v15, v15
	v_cvt_i32_f32_sdwa v17, v17 dst_sel:WORD_1 dst_unused:UNUSED_PAD src0_sel:DWORD
	v_cvt_i32_f32_e32 v18, v18
	v_lshlrev_b32_e32 v16, 8, v16
	v_and_b32_e32 v16, 0xff00, v16
	v_and_b32_e32 v17, 0xff0000, v17
	v_perm_b32 v15, v18, v15, s15
	v_or3_b32 v16, v15, v16, v17
	v_mul_f32_e32 v17, v47, v28
	v_mul_f32_e32 v15, v47, v45
	v_mul_f32_e32 v18, v47, v46
	v_mul_f32_e32 v19, v47, v29
	v_med3_f32 v17, v17, s14, v0
	v_med3_f32 v15, v15, s14, v0
	v_rndne_f32_e32 v17, v17
	v_med3_f32 v18, v18, s14, v0
	v_med3_f32 v19, v19, s14, v0
	v_rndne_f32_e32 v15, v15
	v_cvt_i32_f32_e32 v17, v17
	v_rndne_f32_e32 v18, v18
	v_rndne_f32_e32 v19, v19
	v_cvt_i32_f32_e32 v15, v15
	v_cvt_i32_f32_sdwa v18, v18 dst_sel:WORD_1 dst_unused:UNUSED_PAD src0_sel:DWORD
	v_cvt_i32_f32_e32 v19, v19
	v_lshlrev_b32_e32 v17, 8, v17
	v_and_b32_e32 v17, 0xff00, v17
	v_and_b32_e32 v18, 0xff0000, v18
	v_perm_b32 v15, v19, v15, s15
	v_or3_b32 v17, v15, v17, v18
	global_store_dwordx2 v[4:5], v[16:17], off offset:512
	s_and_saveexec_b64 s[2:3], s[0:1]
	s_cbranch_execz .LBB0_573
	v_mov_b32_e32 v15, v97
	v_mul_f32_e32 v14, 0x3c010204, v14
	v_fmamk_f32 v15, v15, 0x3a000000, v13
	v_mul_f32_e32 v16, 0x4b800000, v15
	v_cmp_gt_f32_e32 vcc, s16, v15
	s_nop 1
	v_cndmask_b32_e32 v15, v15, v16, vcc
	v_rsq_f32_e32 v15, v15
	s_nop 0
	v_mul_f32_e32 v16, 0x45800000, v15
	v_cndmask_b32_e32 v15, v15, v16, vcc
	v_mul_f32_e32 v14, v14, v15
	global_store_dword v1, v14, s[4:5]
	s_branch .LBB0_573
